# GEMM phases: static s_setprio 1 for the workgroup placed second on its CU
# baseline (speedup 1.0000x reference)
.LBB0_202:
	s_or_b64 exec, exec, s[0:1]
	s_mov_b32 s0, s73
	s_mov_b32 s3, s96
	s_waitcnt lgkmcnt(0)
	s_barrier
	s_getreg_b32 s98, hwreg(HW_REG_LDS_ALLOC, 0, 12)
	s_cmp_eq_u32 s98, 0
	s_cbranch_scc1 .Lgp2_0
	s_setprio 1
.Lgp2_0:
	v_mov_b32_e32 v0, v226
	s_ashr_i32 s2, s0, 3
	s_cmpk_gt_i32 s2, 0xdb
	v_readfirstlane_b32 s1, v0
	s_cbranch_scc1 .LBB0_467
	v_bfe_u32 v1, v0, 4, 2
	v_lshrrev_b32_e32 v2, 2, v0
	v_bitop3_b32 v2, v1, v2, 3 bitop3:0x78
	v_lshlrev_b32_e32 v2, 3, v2
	v_lshlrev_b32_e32 v3, 5, v0
	s_mov_b32 s4, 0x7ffff1e0
	v_and_or_b32 v4, v3, s4, v2
	s_movk_i32 s4, 0x9e0
	v_and_b32_e32 v128, 15, v0
	v_and_b32_e32 v129, 0xffffff80, v0
	v_and_b32_e32 v143, 64, v0
	v_and_or_b32 v2, v3, s4, v2
	s_ashr_i32 s4, s1, 6
	v_bitop3_b32 v3, v1, v0, 3 bitop3:0x78
	v_bfe_u32 v0, v0, 2, 4
	s_andn2_b32 s1, s1, 63
	s_ashr_i32 s3, s3, 3
	v_or_b32_e32 v145, s1, v0
	s_lshl_b32 s1, s4, 11
	s_and_b32 s26, s0, 7
	s_lshl_b32 s27, s4, 12
	s_sub_i32 s28, 0, s1
	s_lshl_b32 s29, s2, 6
	s_lshl_b32 s30, s3, 6
	v_lshlrev_b32_e32 v130, 4, v3
	v_mov_b32_e32 v131, 0
	v_readlane_b32 s36, v241, 1
	s_bitcmp1_b32 s0, 3
	v_lshl_add_u64 v[132:133], s[78:79], 0, v[130:131]
	v_lshl_add_u64 v[134:135], s[86:87], 0, v[130:131]
	v_lshlrev_b32_e32 v130, 2, v143
	v_readlane_b32 s42, v241, 7
	v_readlane_b32 s44, v241, 9
	v_readlane_b32 s45, v241, 10
	s_cselect_b64 s[12:13], -1, 0
	s_bitcmp1_b32 s3, 0
	v_lshlrev_b32_e32 v142, 1, v4
	v_lshlrev_b32_e32 v2, 1, v2
	v_lshl_or_b32 v146, s4, 5, v0
	v_lshlrev_b32_e32 v147, 2, v1
	v_readlane_b32 s37, v241, 2
	v_readlane_b32 s38, v241, 3
	v_readlane_b32 s39, v241, 4
	v_readlane_b32 s40, v241, 5
	v_readlane_b32 s41, v241, 6
	v_readlane_b32 s43, v241, 8
	v_readlane_b32 s46, v241, 11
	v_readlane_b32 s47, v241, 12
	v_lshl_add_u64 v[0:1], s[44:45], 0, v[130:131]
	v_lshlrev_b32_e32 v130, 2, v128
	s_cselect_b64 s[14:15], -1, 0
	s_add_i32 s42, s27, s28
	v_or_b32_e32 v144, 0x4000, v2
	s_mul_i32 s26, s26, 10
	s_mov_b32 s11, 0
	v_add_u32_e32 v148, 0x6000, v142
	v_or_b32_e32 v149, 0xa000, v2
	v_lshl_add_u64 v[136:137], v[0:1], 0, v[130:131]
	s_mov_b64 s[16:17], 0x8000
	s_add_i32 s31, s27, 0x400
	s_add_i32 s33, s27, 0x800
	s_add_i32 s34, s27, 0xc00
	s_add_i32 s35, s42, 0x4000
	s_add_i32 s36, s42, 0x4400
	s_add_i32 s37, s27, 0x6000
	s_mov_b64 s[18:19], 0x8040
	s_add_i32 s38, s27, 0x6400
	s_add_i32 s39, s27, 0x6800
	s_add_i32 s40, s27, 0x6c00
	s_add_i32 s41, s42, 0xa000
	s_add_i32 s42, s42, 0xa400
	s_mov_b64 s[20:21], 0x80
	s_mov_b64 s[22:23], 0x8080
	s_movk_i32 s43, 0x1520
	v_lshlrev_b32_e32 v130, 1, v128
	s_movk_i32 s44, 0xa90
	s_movk_i32 s45, 0x7fff
	s_movk_i32 s46, 0x1000
	s_mov_b32 s47, 0x5000000
	v_readlane_b32 s48, v241, 13
	v_readlane_b32 s49, v241, 14
	v_readlane_b32 s50, v241, 15
	v_readlane_b32 s51, v241, 16
	s_branch .LBB0_205

.LBB0_467:
	s_waitcnt vmcnt(0)
	s_waitcnt vmcnt(0) lgkmcnt(0)
	s_setprio 0
	s_barrier
	s_and_saveexec_b64 s[0:1], s[74:75]
	s_cbranch_execz .LBB0_519
	v_mov_b32_e32 v0, 0x12000
	s_waitcnt vmcnt(0) expcnt(0) lgkmcnt(0)
	ds_read_b32 v2, v0
	v_mov_b32_e32 v0, 0x12004
	ds_read_b32 v0, v0
	s_waitcnt lgkmcnt(1)
	v_cmp_ne_u32_e32 vcc, 0, v2
	s_cbranch_vccnz .LBB0_483
	s_add_u32 s4, s80, 0x1000
	s_addc_u32 s5, s81, 0
	s_add_u32 s6, s80, 0x1100
	s_addc_u32 s7, s81, 0
	s_add_u32 s8, s80, 0x1200
	v_readlane_b32 s2, v241, 0
	s_addc_u32 s9, s81, 0
	s_mul_i32 s2, s97, s2
	s_add_u32 s10, s80, 0x1300
	s_mul_i32 s2, s2, s96
	s_addc_u32 s11, s81, 0
	s_mov_b32 s3, 1
	v_mov_b32_e32 v16, 0
	s_branch .LBB0_471

.LBB0_630:
	s_or_b64 exec, exec, s[0:1]
	s_mov_b32 s0, s73
	s_mov_b32 s1, s96
	s_waitcnt lgkmcnt(0)
	s_barrier
	s_getreg_b32 s98, hwreg(HW_REG_LDS_ALLOC, 0, 12)
	s_cmp_eq_u32 s98, 0
	s_cbranch_scc1 .Lgp2_1
	s_setprio 1
.Lgp2_1:
	v_mov_b32_e32 v0, v226
	s_ashr_i32 s2, s0, 3
	s_cmpk_gt_i32 s2, 0xc7
	v_readfirstlane_b32 s4, v0
	s_cbranch_scc1 .LBB0_689
	s_ashr_i32 s3, s1, 3
	s_ashr_i32 s1, s4, 1
	v_bfe_u32 v1, v0, 2, 4
	s_andn2_b32 s1, s1, 31
	v_or_b32_e32 v80, s1, v1
	v_bfe_u32 v1, v0, 4, 2
	v_lshrrev_b32_e32 v2, 2, v0
	v_bitop3_b32 v3, v1, v0, 3 bitop3:0x78
	v_bitop3_b32 v2, v1, v2, 3 bitop3:0x78
	s_and_b32 s33, s0, 7
	v_and_b32_e32 v4, 15, v0
	v_lshlrev_b32_e32 v70, 4, v3
	v_ashrrev_i32_e32 v3, 1, v0
	s_movk_i32 s0, 0xffc0
	v_lshlrev_b32_e32 v2, 4, v2
	v_and_or_b32 v81, v3, s0, v4
	v_and_b32_e32 v3, 64, v0
	v_lshlrev_b32_e32 v0, 6, v0
	s_movk_i32 s0, 0x13c0
	v_readlane_b32 s52, v241, 17
	v_mov_b32_e32 v71, 0
	s_lshl_b32 s36, s1, 6
	v_lshl_or_b32 v82, v81, 6, v2
	v_and_or_b32 v0, v0, s0, v2
	v_readlane_b32 s54, v241, 19
	v_readlane_b32 s55, v241, 20
	s_mul_i32 s33, s33, 20
	v_lshl_add_u64 v[72:73], s[84:85], 0, v[70:71]
	v_lshl_add_u64 v[74:75], s[76:77], 0, v[70:71]
	v_or_b32_e32 v83, 0x2000, v0
	v_lshl_or_b32 v84, v1, 2, v3
	v_add_u32_e32 v85, 0x4000, v82
	v_or_b32_e32 v86, 0x6000, v0
	v_add_u32_e32 v87, 0x8000, v82
	v_or_b32_e32 v88, 0xa000, v0
	s_lshl_b32 s37, s2, 5
	s_lshl_b32 s38, s3, 5
	s_mov_b64 s[0:1], 0x2000
	s_add_i32 s39, s36, 0x400
	s_add_i32 s40, s36, 0x2000
	s_add_i32 s41, s36, 0x2400
	s_add_i32 s42, s36, 0x4000
	s_mov_b64 s[4:5], 0x2040
	s_add_i32 s43, s36, 0x4400
	s_add_i32 s44, s36, 0x6000
	s_add_i32 s45, s36, 0x6400
	s_mov_b64 s[6:7], 0x2080
	s_mov_b64 s[8:9], 0x80
	s_add_i32 s46, s36, 0x8000
	s_add_i32 s47, s36, 0x8400
	s_add_i32 s48, s36, 0xa000
	s_add_i32 s49, s36, 0xa400
	s_mov_b64 s[10:11], 0x20c0
	s_mov_b64 s[12:13], 0xc0
	s_mov_b64 s[14:15], 0x2100
	s_mov_b64 s[16:17], 0x100
	s_mov_b64 s[18:19], 0x2140
	s_mov_b64 s[20:21], 0x140
	s_mov_b64 s[22:23], 0x2180
	s_mov_b64 s[24:25], 0x180
	s_mov_b64 s[26:27], 0x21c0
	s_mov_b64 s[28:29], 0x1c0
	s_movk_i32 s50, 0x1ff
	s_movk_i32 s51, 0xa00
	v_mov_b64_e32 v[76:77], s[54:55]
	s_movk_i32 s52, 0x7fff
	v_mov_b32_e32 v89, 1
	v_readlane_b32 s53, v241, 18
	v_readlane_b32 s56, v241, 21
	v_readlane_b32 s57, v241, 22
	v_readlane_b32 s58, v241, 23
	v_readlane_b32 s59, v241, 24
	s_branch .LBB0_633

.LBB0_1403:
	s_or_b64 exec, exec, s[0:1]
	s_mov_b32 s0, s74
	s_mov_b32 s1, s76
	s_waitcnt lgkmcnt(0)
	s_barrier
	s_getreg_b32 s98, hwreg(HW_REG_LDS_ALLOC, 0, 12)
	s_cmp_eq_u32 s98, 0
	s_cbranch_scc1 .Lgp2_2
	s_setprio 1
.Lgp2_2:
	v_mov_b32_e32 v0, v226
	s_ashr_i32 s2, s0, 3
	s_cmpk_gt_i32 s2, 0x9f
	v_readfirstlane_b32 s4, v0
	s_cbranch_scc1 .LBB0_1408
	s_ashr_i32 s3, s1, 3
	s_ashr_i32 s1, s4, 1
	v_bfe_u32 v1, v0, 2, 4
	s_andn2_b32 s1, s1, 31
	v_or_b32_e32 v85, s1, v1
	v_bfe_u32 v1, v0, 4, 2
	v_lshrrev_b32_e32 v2, 2, v0
	v_bitop3_b32 v2, v1, v2, 3 bitop3:0x78
	v_bitop3_b32 v4, v1, v0, 3 bitop3:0x78
	v_lshlrev_b32_e32 v3, 4, v2
	v_lshlrev_b32_e32 v2, 3, v4
	v_lshlrev_b32_e32 v68, 4, v4
	v_ashrrev_i32_e32 v4, 1, v0
	v_and_b32_e32 v84, 15, v0
	v_and_b32_e32 v86, 0xffffffc0, v4
	s_and_b32 s9, s0, 7
	v_or_b32_e32 v4, v86, v84
	v_and_b32_e32 v87, 64, v0
	v_lshlrev_b32_e32 v0, 6, v0
	s_movk_i32 s0, 0x13c0
	v_readlane_b32 s16, v241, 17
	v_readlane_b32 s36, v241, 1
	v_mov_b32_e32 v69, 0
	s_lshl_b32 s14, s1, 6
	v_lshl_or_b32 v88, v4, 6, v3
	v_and_or_b32 v3, v0, s0, v3
	v_lshlrev_b32_e32 v0, 2, v1
	v_readlane_b32 s17, v241, 18
	v_readlane_b32 s18, v241, 19
	v_readlane_b32 s19, v241, 20
	v_readlane_b32 s20, v241, 21
	v_readlane_b32 s21, v241, 22
	v_readlane_b32 s22, v241, 23
	v_readlane_b32 s23, v241, 24
	v_readlane_b32 s46, v241, 11
	v_readlane_b32 s47, v241, 12
	s_mul_i32 s9, s9, 20
	v_lshl_add_u64 v[70:71], s[88:89], 0, v[68:69]
	v_or_b32_e32 v89, 0x2000, v3
	v_add_u32_e32 v90, 0x4000, v88
	v_or_b32_e32 v91, 0x6000, v3
	v_lshl_add_u64 v[72:73], s[20:21], 0, v[68:69]
	s_lshl_b32 s15, s2, 5
	s_lshl_b32 s16, s3, 5
	s_add_i32 s17, s14, 0x400
	s_add_i32 s18, s14, 0x2000
	s_add_i32 s19, s14, 0x2400
	s_add_i32 s20, s14, 0x4000
	s_add_i32 s21, s14, 0x4400
	s_add_i32 s22, s14, 0x6000
	s_add_i32 s23, s14, 0x6400
	s_mov_b32 s1, 0
	v_lshlrev_b32_e32 v68, 1, v2
	s_mov_b64 s[4:5], 0x80
	s_mov_b64 s[6:7], 0xc0
	v_mov_b64_e32 v[74:75], s[46:47]
	v_lshlrev_b32_e32 v76, 2, v0
	v_mov_b32_e32 v77, v69
	s_mov_b32 s8, 0x3fb504f3
	v_readlane_b32 s37, v241, 2
	v_readlane_b32 s38, v241, 3
	v_readlane_b32 s39, v241, 4
	v_readlane_b32 s40, v241, 5
	v_readlane_b32 s41, v241, 6
	v_readlane_b32 s42, v241, 7
	v_readlane_b32 s43, v241, 8
	v_readlane_b32 s44, v241, 9
	v_readlane_b32 s45, v241, 10
	v_readlane_b32 s48, v241, 13
	v_readlane_b32 s49, v241, 14
	v_readlane_b32 s50, v241, 15
	v_readlane_b32 s51, v241, 16
	s_waitcnt vmcnt(0)

.LBB0_1408:
	s_waitcnt vmcnt(0)
	s_waitcnt lgkmcnt(0)
	s_setprio 0
	s_barrier
	s_and_saveexec_b64 s[0:1], s[72:73]
	s_cbranch_execz .LBB0_1460
	v_mov_b32_e32 v0, 0x12000
	s_waitcnt vmcnt(0) expcnt(0) lgkmcnt(0)
	ds_read_b32 v2, v0
	v_mov_b32_e32 v0, 0x12004
	ds_read_b32 v0, v0
	s_waitcnt lgkmcnt(1)
	v_cmp_ne_u32_e32 vcc, 0, v2
	s_cbranch_vccnz .LBB0_1424
	s_add_u32 s4, s80, 0x1000
	s_addc_u32 s5, s81, 0
	s_add_u32 s6, s80, 0x1100
	s_addc_u32 s7, s81, 0
	s_add_u32 s8, s80, 0x1200
	s_addc_u32 s9, s81, 0
	s_mul_i32 s2, s77, s78
	s_add_u32 s10, s80, 0x1300
	s_mul_i32 s2, s2, s76
	s_addc_u32 s11, s81, 0
	s_mov_b32 s3, 1
	v_mov_b32_e32 v16, 0
	s_branch .LBB0_1412

.LBB0_1517:
	s_or_b64 exec, exec, s[0:1]
	s_mov_b32 s0, s74
	s_mov_b32 s3, s76
	s_waitcnt lgkmcnt(0)
	s_barrier
	s_getreg_b32 s98, hwreg(HW_REG_LDS_ALLOC, 0, 12)
	s_cmp_eq_u32 s98, 0
	s_cbranch_scc1 .Lgp2_3
	s_setprio 1
.Lgp2_3:
	v_mov_b32_e32 v0, v226
	s_ashr_i32 s2, s0, 3
	s_cmpk_gt_i32 s2, 0x1b7
	v_readfirstlane_b32 s1, v0
	s_cbranch_scc1 .LBB0_1522
	v_bfe_u32 v1, v0, 4, 2
	v_lshrrev_b32_e32 v2, 2, v0
	v_bitop3_b32 v2, v1, v2, 3 bitop3:0x78
	v_lshlrev_b32_e32 v2, 3, v2
	v_lshlrev_b32_e32 v3, 5, v0
	s_mov_b32 s4, 0x7ffff1e0
	v_and_or_b32 v4, v3, s4, v2
	s_movk_i32 s4, 0x9e0
	v_lshlrev_b32_e32 v139, 1, v4
	v_and_or_b32 v2, v3, s4, v2
	s_ashr_i32 s4, s1, 6
	v_bfe_u32 v4, v0, 2, 4
	s_andn2_b32 s1, s1, 63
	s_ashr_i32 s3, s3, 3
	v_or_b32_e32 v142, s1, v4
	s_lshl_b32 s1, s4, 11
	s_and_b32 s16, s0, 7
	s_lshl_b32 s17, s4, 12
	s_sub_i32 s18, 0, s1
	s_lshl_b32 s19, s2, 6
	s_lshl_b32 s20, s3, 6
	v_bitop3_b32 v3, v1, v0, 3 bitop3:0x78
	v_lshlrev_b32_e32 v1, 2, v1
	s_movk_i32 s1, 0xff80
	s_bitcmp1_b32 s0, 3
	v_and_or_b32 v145, v0, s1, v1
	s_cselect_b64 s[0:1], -1, 0
	s_bitcmp1_b32 s3, 0
	v_lshlrev_b32_e32 v2, 1, v2
	v_lshlrev_b32_e32 v128, 4, v3
	v_mov_b32_e32 v129, 0
	v_lshl_or_b32 v143, s4, 5, v4
	s_cselect_b64 s[4:5], -1, 0
	s_add_i32 s31, s17, s18
	v_and_b32_e32 v138, 15, v0
	v_and_b32_e32 v140, 64, v0
	v_or_b32_e32 v141, 0x4000, v2
	s_mul_i32 s16, s16, 10
	v_lshl_add_u64 v[130:131], s[70:71], 0, v[128:129]
	v_lshl_add_u64 v[132:133], s[90:91], 0, v[128:129]
	v_add_u32_e32 v128, 0x6000, v139
	v_or_b32_e32 v144, 0xa000, v2
	s_mov_b64 s[6:7], 0x8000
	s_add_i32 s21, s17, 0x400
	s_add_i32 s22, s17, 0x800
	s_add_i32 s23, s17, 0xc00
	s_add_i32 s24, s31, 0x4000
	s_add_i32 s25, s31, 0x4400
	s_add_i32 s26, s17, 0x6000
	s_mov_b64 s[8:9], 0x8040
	s_add_i32 s27, s17, 0x6400
	s_add_i32 s28, s17, 0x6800
	s_add_i32 s29, s17, 0x6c00
	s_add_i32 s30, s31, 0xa000
	s_add_i32 s31, s31, 0xa400
	s_movk_i32 s33, 0x1600
	s_mov_b64 s[10:11], 0x80
	s_mov_b64 s[12:13], 0x8080
	s_movk_i32 s34, 0x7fff
	s_waitcnt vmcnt(0)

.LBB0_1522:
	s_waitcnt vmcnt(0)
	s_waitcnt vmcnt(0) lgkmcnt(0)
	s_setprio 0
	s_barrier
	s_and_saveexec_b64 s[0:1], s[72:73]
	s_cbranch_execz .LBB0_1574
	v_mov_b32_e32 v0, 0x12000
	s_waitcnt vmcnt(0) expcnt(0) lgkmcnt(0)
	ds_read_b32 v2, v0
	v_mov_b32_e32 v0, 0x12004
	ds_read_b32 v0, v0
	s_waitcnt lgkmcnt(1)
	v_cmp_ne_u32_e32 vcc, 0, v2
	s_cbranch_vccnz .LBB0_1538
	s_add_u32 s4, s80, 0x1000
	s_addc_u32 s5, s81, 0
	s_add_u32 s6, s80, 0x1100
	s_addc_u32 s7, s81, 0
	s_add_u32 s8, s80, 0x1200
	s_addc_u32 s9, s81, 0
	s_mul_i32 s2, s77, s78
	s_add_u32 s10, s80, 0x1300
	s_mul_i32 s2, s2, s76
	s_addc_u32 s11, s81, 0
	s_mov_b32 s3, 1
	v_mov_b32_e32 v16, 0
	s_branch .LBB0_1526

.LBB0_1574:
	s_or_b64 exec, exec, s[0:1]
	s_mov_b32 s0, s74
	s_mov_b32 s14, s76
	s_waitcnt lgkmcnt(0)
	s_barrier
	s_getreg_b32 s98, hwreg(HW_REG_LDS_ALLOC, 0, 12)
	s_cmp_eq_u32 s98, 0
	s_cbranch_scc1 .Lgp2_4
	s_setprio 1
.Lgp2_4:
	v_mov_b32_e32 v0, v226
	s_ashr_i32 s2, s0, 3
	s_cmpk_gt_i32 s2, 0x9f
	v_readfirstlane_b32 s1, v0
	s_cbranch_scc1 .LBB0_1579
	s_ashr_i32 s1, s1, 1
	v_bfe_u32 v1, v0, 2, 4
	s_andn2_b32 s1, s1, 31
	v_or_b32_e32 v83, s1, v1
	v_bfe_u32 v1, v0, 4, 2
	v_bitop3_b32 v3, v1, v0, 3 bitop3:0x78
	v_lshrrev_b32_e32 v2, 2, v0
	v_lshlrev_b32_e32 v68, 4, v3
	v_ashrrev_i32_e32 v3, 1, v0
	v_and_b32_e32 v82, 15, v0
	v_bitop3_b32 v2, v1, v2, 3 bitop3:0x78
	v_and_b32_e32 v84, 0xffffffc0, v3
	s_lshr_b32 s15, s0, 3
	v_lshlrev_b32_e32 v2, 4, v2
	s_and_b32 s18, s0, 7
	v_or_b32_e32 v3, v84, v82
	v_and_b32_e32 v85, 64, v0
	v_lshlrev_b32_e32 v0, 6, v0
	s_movk_i32 s0, 0x13c0
	v_readlane_b32 s4, v241, 17
	v_readlane_b32 s36, v241, 1
	s_ashr_i32 s3, s14, 3
	v_mov_b32_e32 v69, 0
	s_lshl_b32 s19, s1, 6
	v_lshl_or_b32 v86, v3, 6, v2
	v_and_or_b32 v2, v0, s0, v2
	v_lshlrev_b32_e32 v0, 2, v1
	v_readlane_b32 s5, v241, 18
	v_readlane_b32 s6, v241, 19
	v_readlane_b32 s7, v241, 20
	v_readlane_b32 s8, v241, 21
	v_readlane_b32 s9, v241, 22
	v_readlane_b32 s10, v241, 23
	v_readlane_b32 s11, v241, 24
	v_readlane_b32 s46, v241, 11
	v_readlane_b32 s47, v241, 12
	s_mul_i32 s18, s18, 20
	v_lshl_add_u64 v[70:71], s[92:93], 0, v[68:69]
	v_or_b32_e32 v87, 0x2000, v2
	v_add_u32_e32 v88, 0x8000, v86
	v_or_b32_e32 v89, 0xa000, v2
	v_lshl_add_u64 v[72:73], s[4:5], 0, v[68:69]
	s_lshl_b32 s20, s2, 5
	s_lshl_b32 s21, s3, 5
	s_movk_i32 s22, 0x1600
	s_mov_b64 s[0:1], 0x16000
	s_add_i32 s23, s19, 0x400
	s_add_i32 s24, s19, 0x2000
	s_add_i32 s25, s19, 0x2400
	s_add_i32 s26, s19, 0x4000
	s_mov_b64 s[4:5], 0x16040
	s_add_i32 s27, s19, 0x4400
	s_add_i32 s28, s19, 0x6000
	s_add_i32 s29, s19, 0x6400
	s_mov_b64 s[6:7], 0x80
	s_mov_b64 s[8:9], 0x16080
	s_mov_b64 s[10:11], 0xc0
	s_mov_b64 s[12:13], 0x160c0
	s_lshr_b32 s30, s14, 3
	v_mov_b64_e32 v[74:75], s[46:47]
	v_lshlrev_b32_e32 v68, 2, v0
	s_mov_b32 s14, 0x3fb504f3
	v_readlane_b32 s37, v241, 2
	v_readlane_b32 s38, v241, 3
	v_readlane_b32 s39, v241, 4
	v_readlane_b32 s40, v241, 5
	v_readlane_b32 s41, v241, 6
	v_readlane_b32 s42, v241, 7
	v_readlane_b32 s43, v241, 8
	v_readlane_b32 s44, v241, 9
	v_readlane_b32 s45, v241, 10
	v_readlane_b32 s48, v241, 13
	v_readlane_b32 s49, v241, 14
	v_readlane_b32 s50, v241, 15
	v_readlane_b32 s51, v241, 16
	s_waitcnt vmcnt(0)

.Lgp2_5:
	v_mov_b32_e32 v0, v226
	s_ashr_i32 s2, s0, 3
	s_cmpk_gt_i32 s2, 0xdb
	v_readfirstlane_b32 s1, v0
	s_cbranch_scc1 .LBB0_1953
	v_bfe_u32 v1, v0, 4, 2
	v_lshrrev_b32_e32 v2, 2, v0
	v_bitop3_b32 v2, v1, v2, 3 bitop3:0x78
	v_lshlrev_b32_e32 v2, 3, v2
	v_lshlrev_b32_e32 v3, 5, v0
	s_mov_b32 s4, 0x7ffff1e0
	v_and_or_b32 v4, v3, s4, v2
	s_movk_i32 s4, 0x9e0
	v_and_b32_e32 v128, 15, v0
	v_and_b32_e32 v129, 0xffffff80, v0
	v_and_b32_e32 v145, 64, v0
	v_and_or_b32 v2, v3, s4, v2
	s_ashr_i32 s6, s1, 6
	v_bitop3_b32 v3, v1, v0, 3 bitop3:0x78
	v_bfe_u32 v0, v0, 2, 4
	s_andn2_b32 s1, s1, 63
	s_ashr_i32 s3, s3, 3
	v_or_b32_e32 v147, s1, v0
	s_lshl_b32 s1, s6, 11
	s_and_b32 s22, s0, 7
	s_lshl_b32 s23, s6, 12
	s_sub_i32 s24, 0, s1
	s_lshl_b32 s25, s2, 6
	s_lshl_b32 s26, s3, 6
	v_lshlrev_b32_e32 v130, 4, v3
	v_mov_b32_e32 v131, 0
	v_readlane_b32 s36, v241, 1
	s_bitcmp1_b32 s0, 3
	v_lshl_add_u64 v[132:133], s[70:71], 0, v[130:131]
	v_lshl_add_u64 v[134:135], s[86:87], 0, v[130:131]
	v_lshlrev_b32_e32 v130, 2, v145
	v_readlane_b32 s38, v241, 3
	v_readlane_b32 s44, v241, 9
	v_readlane_b32 s45, v241, 10
	s_cselect_b64 s[12:13], -1, 0
	s_bitcmp1_b32 s3, 0
	v_lshlrev_b32_e32 v144, 1, v4
	v_lshlrev_b32_e32 v2, 1, v2
	v_lshl_or_b32 v148, s6, 5, v0
	s_mov_b64 s[4:5], 0x580000
	v_lshlrev_b32_e32 v149, 2, v1
	v_readlane_b32 s37, v241, 2
	v_readlane_b32 s39, v241, 4
	v_readlane_b32 s40, v241, 5
	v_readlane_b32 s41, v241, 6
	v_readlane_b32 s42, v241, 7
	v_readlane_b32 s43, v241, 8
	v_lshl_add_u64 v[0:1], s[44:45], 0, v[130:131]
	v_lshlrev_b32_e32 v130, 2, v128
	s_cselect_b64 s[14:15], -1, 0
	s_add_i32 s38, s23, s24
	v_or_b32_e32 v146, 0x4000, v2
	s_mul_i32 s22, s22, 10
	v_lshl_add_u64 v[136:137], v[134:135], 0, s[4:5]
	s_mov_b32 s11, 0
	v_add_u32_e32 v150, 0x6000, v144
	v_or_b32_e32 v151, 0xa000, v2
	v_lshl_add_u64 v[138:139], v[0:1], 0, v[130:131]
	s_mov_b64 s[16:17], 0x8000
	s_add_i32 s27, s23, 0x400
	s_add_i32 s28, s23, 0x800
	s_add_i32 s29, s23, 0xc00
	s_add_i32 s30, s38, 0x4000
	s_add_i32 s31, s38, 0x4400
	s_add_i32 s33, s23, 0x6000
	s_mov_b64 s[18:19], 0x8040
	s_add_i32 s34, s23, 0x6400
	s_add_i32 s35, s23, 0x6800
	s_add_i32 s36, s23, 0x6c00
	s_add_i32 s37, s38, 0xa000
	s_add_i32 s38, s38, 0xa400
	s_movk_i32 s39, 0x1520
	v_lshlrev_b32_e32 v130, 1, v128
	s_movk_i32 s40, 0xa90
	s_movk_i32 s41, 0x7fff
	s_movk_i32 s42, 0x1000
	s_mov_b32 s43, 0x5000000
	v_readlane_b32 s46, v241, 11
	v_readlane_b32 s47, v241, 12
	v_readlane_b32 s48, v241, 13
	v_readlane_b32 s49, v241, 14
	v_readlane_b32 s50, v241, 15
	v_readlane_b32 s51, v241, 16
	s_branch .LBB0_1691

.LBB0_2116:
	s_or_b64 exec, exec, s[0:1]
	s_mov_b32 s1, s76
	s_mov_b32 s0, s74
	s_waitcnt lgkmcnt(0)
	s_barrier
	s_getreg_b32 s98, hwreg(HW_REG_LDS_ALLOC, 0, 12)
	s_cmp_eq_u32 s98, 0
	s_cbranch_scc1 .Lgp2_6
	s_setprio 1
.Lgp2_6:
	v_mov_b32_e32 v0, v226
	s_ashr_i32 s2, s0, 3
	s_cmpk_gt_i32 s2, 0xc7
	v_readfirstlane_b32 s4, v0
	s_cbranch_scc1 .LBB0_2175
	s_ashr_i32 s3, s1, 3
	s_ashr_i32 s1, s4, 1
	v_bfe_u32 v1, v0, 2, 4
	s_and_b32 s4, s1, 0xffffffe0
	v_or_b32_e32 v80, s4, v1
	v_bfe_u32 v1, v0, 4, 2
	v_lshrrev_b32_e32 v2, 2, v0
	v_bitop3_b32 v2, v1, v2, 3 bitop3:0x78
	v_lshlrev_b32_e32 v4, 4, v2
	v_bitop3_b32 v2, v1, v0, 3 bitop3:0x78
	v_lshlrev_b32_e32 v70, 4, v2
	v_mov_b32_e32 v71, 0
	s_and_b32 s33, s0, 7
	v_lshl_add_u64 v[2:3], s[84:85], 0, v[70:71]
	s_mov_b64 s[0:1], 0xa0000
	v_and_b32_e32 v5, 15, v0
	v_lshl_add_u64 v[72:73], v[2:3], 0, s[0:1]
	v_ashrrev_i32_e32 v2, 1, v0
	s_movk_i32 s0, 0xffc0
	v_and_or_b32 v81, v2, s0, v5
	v_and_b32_e32 v2, 64, v0
	v_lshlrev_b32_e32 v0, 6, v0
	s_movk_i32 s0, 0x13c0
	v_readlane_b32 s52, v241, 17
	s_lshl_b32 s36, s4, 6
	v_lshl_or_b32 v82, v81, 6, v4
	v_and_or_b32 v0, v0, s0, v4
	v_readlane_b32 s54, v241, 19
	v_readlane_b32 s55, v241, 20
	s_mul_i32 s33, s33, 20
	v_lshl_add_u64 v[74:75], s[68:69], 0, v[70:71]
	v_or_b32_e32 v83, 0x2000, v0
	v_lshl_or_b32 v84, v1, 2, v2
	v_add_u32_e32 v85, 0x4000, v82
	v_or_b32_e32 v86, 0x6000, v0
	v_add_u32_e32 v87, 0x8000, v82
	v_or_b32_e32 v88, 0xa000, v0
	s_lshl_b32 s37, s2, 5
	s_lshl_b32 s38, s3, 5
	s_mov_b64 s[0:1], 0x2000
	s_add_i32 s39, s36, 0x400
	s_add_i32 s40, s36, 0x2000
	s_add_i32 s41, s36, 0x2400
	s_add_i32 s42, s36, 0x4000
	s_mov_b64 s[4:5], 0x2040
	s_add_i32 s43, s36, 0x4400
	s_add_i32 s44, s36, 0x6000
	s_add_i32 s45, s36, 0x6400
	s_mov_b64 s[6:7], 0x2080
	s_mov_b64 s[8:9], 0x80
	s_add_i32 s46, s36, 0x8000
	s_add_i32 s47, s36, 0x8400
	s_add_i32 s48, s36, 0xa000
	s_add_i32 s49, s36, 0xa400
	s_mov_b64 s[10:11], 0x20c0
	s_mov_b64 s[12:13], 0xc0
	s_mov_b64 s[14:15], 0x2100
	s_mov_b64 s[16:17], 0x100
	s_mov_b64 s[18:19], 0x2140
	s_mov_b64 s[20:21], 0x140
	s_mov_b64 s[22:23], 0x2180
	s_mov_b64 s[24:25], 0x180
	s_mov_b64 s[26:27], 0x21c0
	s_mov_b64 s[28:29], 0x1c0
	s_movk_i32 s50, 0x1ff
	s_movk_i32 s51, 0xa00
	v_mov_b64_e32 v[76:77], s[54:55]
	s_movk_i32 s52, 0x7fff
	v_mov_b32_e32 v89, 1
	v_readlane_b32 s53, v241, 18
	v_readlane_b32 s56, v241, 21
	v_readlane_b32 s57, v241, 22
	v_readlane_b32 s58, v241, 23
	v_readlane_b32 s59, v241, 24
	s_branch .LBB0_2119

.LBB0_2889:
	s_or_b64 exec, exec, s[0:1]
	s_mov_b32 s0, s70
	s_mov_b32 s1, s68
	s_waitcnt lgkmcnt(0)
	s_barrier
	s_getreg_b32 s98, hwreg(HW_REG_LDS_ALLOC, 0, 12)
	s_cmp_eq_u32 s98, 0
	s_cbranch_scc1 .Lgp2_7
	s_setprio 1
.Lgp2_7:
	v_mov_b32_e32 v0, v226
	s_ashr_i32 s2, s0, 3
	s_cmpk_gt_i32 s2, 0x9f
	v_readfirstlane_b32 s4, v0
	s_cbranch_scc1 .LBB0_2894
	s_ashr_i32 s3, s1, 3
	s_ashr_i32 s1, s4, 1
	v_bfe_u32 v1, v0, 2, 4
	s_andn2_b32 s1, s1, 31
	v_or_b32_e32 v83, s1, v1
	v_bfe_u32 v1, v0, 4, 2
	v_lshrrev_b32_e32 v2, 2, v0
	v_bitop3_b32 v2, v1, v2, 3 bitop3:0x78
	v_bitop3_b32 v4, v1, v0, 3 bitop3:0x78
	v_lshlrev_b32_e32 v3, 4, v2
	v_lshlrev_b32_e32 v2, 3, v4
	v_lshlrev_b32_e32 v68, 4, v4
	v_ashrrev_i32_e32 v4, 1, v0
	v_and_b32_e32 v82, 15, v0
	v_and_b32_e32 v84, 0xffffffc0, v4
	s_and_b32 s23, s0, 7
	v_or_b32_e32 v4, v84, v82
	v_and_b32_e32 v85, 64, v0
	v_lshlrev_b32_e32 v0, 6, v0
	s_movk_i32 s0, 0x13c0
	v_readlane_b32 s4, v241, 17
	v_readlane_b32 s44, v241, 1
	v_mov_b32_e32 v69, 0
	s_lshl_b32 s28, s1, 6
	v_lshl_or_b32 v86, v4, 6, v3
	v_and_or_b32 v3, v0, s0, v3
	v_lshlrev_b32_e32 v0, 2, v1
	v_readlane_b32 s5, v241, 18
	v_readlane_b32 s6, v241, 19
	v_readlane_b32 s7, v241, 20
	v_readlane_b32 s8, v241, 21
	v_readlane_b32 s9, v241, 22
	v_readlane_b32 s11, v241, 24
	v_readlane_b32 s54, v241, 11
	v_readlane_b32 s55, v241, 12
	s_mul_i32 s23, s23, 20
	v_lshl_add_u64 v[70:71], s[88:89], 0, v[68:69]
	s_movk_i32 s29, 0x2000
	v_or_b32_e32 v87, 0x2000, v3
	v_add_u32_e32 v88, 0x4000, v86
	s_movk_i32 s30, 0x6000
	v_or_b32_e32 v89, 0x6000, v3
	v_lshl_add_u64 v[72:73], s[8:9], 0, v[68:69]
	s_lshl_b32 s31, s2, 5
	s_lshl_b32 s33, s3, 5
	s_movk_i32 s34, 0x300
	s_mov_b64 s[0:1], 0x3000
	s_add_i32 s35, s28, 0x400
	s_add_i32 s36, s28, 0x2000
	s_mov_b64 s[4:5], 0x8000
	s_add_i32 s37, s28, 0x2400
	s_add_i32 s38, s28, 0x4000
	s_mov_b64 s[6:7], 0x3040
	s_add_i32 s39, s28, 0x4400
	s_add_i32 s40, s28, 0x6000
	s_mov_b64 s[8:9], 0x8040
	s_add_i32 s41, s28, 0x6400
	s_movk_i32 s42, 0x180
	s_mov_b32 s11, 0
	v_lshlrev_b32_e32 v68, 1, v2
	s_mov_b64 s[12:13], 0x80
	s_mov_b64 s[14:15], 0x8080
	s_mov_b64 s[16:17], 0xc0
	s_mov_b64 s[18:19], 0x80c0
	s_movk_i32 s43, 0xfff
	v_mov_b64_e32 v[74:75], s[54:55]
	v_lshlrev_b32_e32 v76, 2, v0
	v_mov_b32_e32 v77, v69
	s_mov_b64 s[20:21], 0x2000
	s_mov_b32 s22, 0x3fb504f3
	v_readlane_b32 s10, v241, 23
	v_readlane_b32 s45, v241, 2
	v_readlane_b32 s46, v241, 3
	v_readlane_b32 s47, v241, 4
	v_readlane_b32 s48, v241, 5
	v_readlane_b32 s49, v241, 6
	v_readlane_b32 s50, v241, 7
	v_readlane_b32 s51, v241, 8
	v_readlane_b32 s52, v241, 9
	v_readlane_b32 s53, v241, 10
	v_readlane_b32 s56, v241, 13
	v_readlane_b32 s57, v241, 14
	v_readlane_b32 s58, v241, 15
	v_readlane_b32 s59, v241, 16
	s_waitcnt vmcnt(0)

.LBB0_2894:
	s_waitcnt vmcnt(0)
	s_waitcnt lgkmcnt(0)
	s_setprio 0
	s_barrier
	s_and_saveexec_b64 s[0:1], s[74:75]
	s_cbranch_execz .LBB0_2946
	v_mov_b32_e32 v0, 0x12000
	s_waitcnt vmcnt(0) expcnt(0) lgkmcnt(0)
	ds_read_b32 v2, v0
	v_mov_b32_e32 v0, 0x12004
	ds_read_b32 v0, v0
	s_waitcnt lgkmcnt(1)
	v_cmp_ne_u32_e32 vcc, 0, v2
	s_cbranch_vccnz .LBB0_2910
	s_add_u32 s4, s80, 0x1000
	s_addc_u32 s5, s81, 0
	s_add_u32 s6, s80, 0x1100
	s_addc_u32 s7, s81, 0
	s_add_u32 s8, s80, 0x1200
	s_addc_u32 s9, s81, 0
	s_mul_i32 s2, s69, s72
	s_add_u32 s10, s80, 0x1300
	s_mul_i32 s2, s2, s68
	s_addc_u32 s11, s81, 0
	s_mov_b32 s3, 1
	v_mov_b32_e32 v16, 0
	s_branch .LBB0_2898

.LBB0_3003:
	s_or_b64 exec, exec, s[0:1]
	s_mov_b32 s3, s68
	s_mov_b32 s0, s70
	s_waitcnt lgkmcnt(0)
	s_barrier
	s_getreg_b32 s98, hwreg(HW_REG_LDS_ALLOC, 0, 12)
	s_cmp_eq_u32 s98, 0
	s_cbranch_scc1 .Lgp2_8
	s_setprio 1
.Lgp2_8:
	v_mov_b32_e32 v0, v226
	s_ashr_i32 s2, s0, 3
	s_cmpk_gt_i32 s2, 0x1b7
	v_readfirstlane_b32 s1, v0
	s_cbranch_scc1 .LBB0_3008
	v_bfe_u32 v1, v0, 4, 2
	v_lshrrev_b32_e32 v2, 2, v0
	v_bitop3_b32 v2, v1, v2, 3 bitop3:0x78
	v_lshlrev_b32_e32 v2, 3, v2
	v_lshlrev_b32_e32 v3, 5, v0
	s_mov_b32 s4, 0x7ffff1e0
	v_and_or_b32 v4, v3, s4, v2
	s_movk_i32 s4, 0x9e0
	s_waitcnt vmcnt(0)
	v_lshlrev_b32_e32 v139, 1, v4
	v_and_or_b32 v2, v3, s4, v2
	s_ashr_i32 s4, s1, 6
	v_bfe_u32 v4, v0, 2, 4
	s_andn2_b32 s1, s1, 63
	s_ashr_i32 s3, s3, 3
	v_or_b32_e32 v142, s1, v4
	s_lshl_b32 s1, s4, 11
	s_and_b32 s28, s0, 7
	s_lshl_b32 s29, s4, 12
	s_sub_i32 s30, 0, s1
	s_lshl_b32 s31, s2, 6
	s_lshl_b32 s33, s3, 6
	v_bitop3_b32 v3, v1, v0, 3 bitop3:0x78
	v_lshlrev_b32_e32 v1, 2, v1
	s_movk_i32 s1, 0xff80
	s_bitcmp1_b32 s0, 3
	v_and_or_b32 v145, v0, s1, v1
	s_cselect_b64 s[0:1], -1, 0
	s_bitcmp1_b32 s3, 0
	v_lshlrev_b32_e32 v2, 1, v2
	v_lshlrev_b32_e32 v128, 4, v3
	v_mov_b32_e32 v129, 0
	v_lshl_or_b32 v143, s4, 5, v4
	s_cselect_b64 s[4:5], -1, 0
	s_add_i32 s44, s29, s30
	v_readlane_b32 s52, v241, 17
	v_and_b32_e32 v138, 15, v0
	v_and_b32_e32 v140, 64, v0
	v_or_b32_e32 v141, 0x4000, v2
	s_mul_i32 s28, s28, 10
	v_lshl_add_u64 v[130:131], s[78:79], 0, v[128:129]
	v_lshl_add_u64 v[132:133], s[90:91], 0, v[128:129]
	v_add_u32_e32 v128, 0x6000, v139
	v_or_b32_e32 v144, 0xa000, v2
	s_mov_b64 s[6:7], 0x8000
	s_add_i32 s34, s29, 0x400
	s_mov_b64 s[8:9], 0x10000
	s_add_i32 s35, s29, 0x800
	s_mov_b64 s[10:11], 0x18000
	s_add_i32 s36, s29, 0xc00
	s_add_i32 s37, s44, 0x4000
	s_add_i32 s38, s44, 0x4400
	s_add_i32 s39, s29, 0x6000
	s_mov_b64 s[12:13], 0x8040
	s_add_i32 s40, s29, 0x6400
	s_mov_b64 s[14:15], 0x10040
	s_add_i32 s41, s29, 0x6800
	s_mov_b64 s[16:17], 0x18040
	s_add_i32 s42, s29, 0x6c00
	s_add_i32 s43, s44, 0xa000
	s_add_i32 s44, s44, 0xa400
	s_movk_i32 s45, 0x1600
	s_mov_b64 s[18:19], 0x80
	s_mov_b64 s[20:21], 0x8080
	s_mov_b64 s[22:23], 0x10080
	s_mov_b64 s[24:25], 0x18080
	s_movk_i32 s46, 0x7fff
	v_readlane_b32 s53, v241, 18
	v_readlane_b32 s54, v241, 19
	v_readlane_b32 s55, v241, 20
	v_readlane_b32 s56, v241, 21
	v_readlane_b32 s57, v241, 22
	v_readlane_b32 s58, v241, 23
	v_readlane_b32 s59, v241, 24
	s_waitcnt vmcnt(0)

.LBB0_3008:
	s_waitcnt vmcnt(0)
	s_waitcnt vmcnt(0) lgkmcnt(0)
	s_setprio 0
	s_barrier
	s_and_saveexec_b64 s[0:1], s[74:75]
	v_readlane_b32 s24, v241, 17
	v_readlane_b32 s25, v241, 18
	v_readlane_b32 s26, v241, 19
	v_readlane_b32 s27, v241, 20
	v_readlane_b32 s28, v241, 21
	v_readlane_b32 s29, v241, 22
	v_readlane_b32 s30, v241, 23
	v_readlane_b32 s31, v241, 24
	s_cbranch_execz .LBB0_3060
	v_mov_b32_e32 v0, 0x12000
	s_waitcnt vmcnt(0) expcnt(0) lgkmcnt(0)
	ds_read_b32 v2, v0
	v_mov_b32_e32 v0, 0x12004
	ds_read_b32 v0, v0
	s_waitcnt lgkmcnt(1)
	v_cmp_ne_u32_e32 vcc, 0, v2
	s_cbranch_vccnz .LBB0_3024
	s_add_u32 s4, s80, 0x1000
	s_addc_u32 s5, s81, 0
	s_add_u32 s6, s80, 0x1100
	s_addc_u32 s7, s81, 0
	s_add_u32 s8, s80, 0x1200
	s_addc_u32 s9, s81, 0
	s_mul_i32 s2, s69, s72
	s_add_u32 s10, s80, 0x1300
	s_mul_i32 s2, s2, s68
	s_addc_u32 s11, s81, 0
	s_mov_b32 s3, 1
	v_mov_b32_e32 v16, 0
	s_branch .LBB0_3012

.LBB0_3060:
	s_or_b64 exec, exec, s[0:1]
	s_mov_b32 s0, s70
	s_mov_b32 s14, s68
	s_waitcnt lgkmcnt(0)
	s_barrier
	s_getreg_b32 s98, hwreg(HW_REG_LDS_ALLOC, 0, 12)
	s_cmp_eq_u32 s98, 0
	s_cbranch_scc1 .Lgp2_9
	s_setprio 1
.Lgp2_9:
	v_mov_b32_e32 v0, v226
	s_ashr_i32 s2, s0, 3
	s_cmpk_gt_i32 s2, 0x9f
	v_readfirstlane_b32 s1, v0
	s_cbranch_scc1 .LBB0_3065
	s_ashr_i32 s1, s1, 1
	v_bfe_u32 v1, v0, 2, 4
	s_andn2_b32 s1, s1, 31
	v_or_b32_e32 v77, s1, v1
	v_bfe_u32 v1, v0, 4, 2
	v_bitop3_b32 v3, v1, v0, 3 bitop3:0x78
	v_lshrrev_b32_e32 v2, 2, v0
	v_lshlrev_b32_e32 v64, 4, v3
	v_ashrrev_i32_e32 v3, 1, v0
	v_and_b32_e32 v76, 15, v0
	v_bitop3_b32 v2, v1, v2, 3 bitop3:0x78
	v_and_b32_e32 v78, 0xffffffc0, v3
	s_lshr_b32 s17, s0, 3
	v_lshlrev_b32_e32 v2, 4, v2
	s_and_b32 s20, s0, 7
	v_or_b32_e32 v3, v78, v76
	v_and_b32_e32 v79, 64, v0
	v_lshlrev_b32_e32 v0, 6, v0
	s_movk_i32 s0, 0x13c0
	v_readlane_b32 s36, v241, 1
	s_ashr_i32 s3, s14, 3
	v_mov_b32_e32 v65, 0
	s_lshl_b32 s21, s1, 6
	v_lshl_or_b32 v80, v3, 6, v2
	v_and_or_b32 v2, v0, s0, v2
	v_lshlrev_b32_e32 v0, 2, v1
	v_readlane_b32 s46, v241, 11
	v_readlane_b32 s47, v241, 12
	s_mul_i32 s20, s20, 20
	v_lshl_add_u64 v[66:67], s[92:93], 0, v[64:65]
	v_or_b32_e32 v81, 0x2000, v2
	v_add_u32_e32 v82, 0x8000, v80
	v_or_b32_e32 v83, 0xa000, v2
	v_lshl_add_u64 v[68:69], s[24:25], 0, v[64:65]
	s_lshl_b32 s22, s2, 5
	s_lshl_b32 s23, s3, 5
	s_movk_i32 s24, 0x1600
	s_mov_b64 s[0:1], 0x16000
	s_add_i32 s25, s21, 0x400
	s_add_i32 s26, s21, 0x2000
	s_add_i32 s27, s21, 0x2400
	s_add_i32 s28, s21, 0x4000
	s_mov_b64 s[4:5], 0x16040
	s_add_i32 s29, s21, 0x4400
	s_movk_i32 s30, 0x6000
	s_add_i32 s31, s21, 0x6000
	s_add_i32 s33, s21, 0x6400
	s_mov_b64 s[6:7], 0x80
	s_mov_b64 s[8:9], 0x16080
	s_mov_b64 s[10:11], 0xc0
	s_mov_b64 s[12:13], 0x160c0
	s_lshr_b32 s34, s14, 3
	s_movk_i32 s35, 0xfff
	v_mov_b64_e32 v[70:71], s[46:47]
	v_lshlrev_b32_e32 v64, 2, v0
	s_mov_b64 s[14:15], 0x5000
	s_movk_i32 s36, 0x5000
	s_mov_b32 s16, 0x3fb504f3
	v_readlane_b32 s37, v241, 2
	v_readlane_b32 s38, v241, 3
	v_readlane_b32 s39, v241, 4
	v_readlane_b32 s40, v241, 5
	v_readlane_b32 s41, v241, 6
	v_readlane_b32 s42, v241, 7
	v_readlane_b32 s43, v241, 8
	v_readlane_b32 s44, v241, 9
	v_readlane_b32 s45, v241, 10
	v_readlane_b32 s48, v241, 13
	v_readlane_b32 s49, v241, 14
	v_readlane_b32 s50, v241, 15
	v_readlane_b32 s51, v241, 16
	s_waitcnt vmcnt(0)
